# diff attention loop: P.V MFMAs interleaved with next key-group exp/pack/rowsum (packed f32 sub and sum kept)
# speedup vs baseline: 1.0069x; 1.0024x over previous
.LBB0_483:
	v_sub_f32_e32 v0, v150, v0
	v_add3_u32 v203, s5, v133, v130
	ds_read_b128 v[224:227], v203 offset:17408
	ds_read_b128 v[228:231], v203 offset:22016
	ds_read_b128 v[232:235], v203 offset:26624
	ds_read_b128 v[236:239], v203 offset:31232
	ds_read_b128 v[240:243], v203 offset:17440
	ds_read_b128 v[244:247], v203 offset:22048
	ds_read_b128 v[248:251], v203 offset:26656
	ds_read_b128 v[204:207], v203 offset:31264
	v_pk_add_f32 v[82:83], v[82:83], v[0:1] op_sel_hi:[1,0] neg_lo:[0,1] neg_hi:[0,1]
	v_pk_add_f32 v[84:85], v[84:85], v[0:1] op_sel_hi:[1,0] neg_lo:[0,1] neg_hi:[0,1]
	v_exp_f32_e32 v82, v82
	v_exp_f32_e32 v83, v83
	v_pk_add_f32 v[86:87], v[86:87], v[0:1] op_sel_hi:[1,0] neg_lo:[0,1] neg_hi:[0,1]
	v_pk_add_f32 v[88:89], v[88:89], v[0:1] op_sel_hi:[1,0] neg_lo:[0,1] neg_hi:[0,1]
	v_exp_f32_e32 v84, v84
	v_exp_f32_e32 v85, v85
	v_exp_f32_e32 v86, v86
	v_exp_f32_e32 v87, v87
	v_exp_f32_e32 v88, v88
	v_exp_f32_e32 v89, v89
	v_cvt_pk_bf16_f32 v170, v82, v83
	v_cvt_pk_bf16_f32 v171, v84, v85
	v_cvt_pk_bf16_f32 v172, v86, v87
	v_cvt_pk_bf16_f32 v173, v88, v89
	v_pk_add_f32 v[186:187], v[82:83], v[84:85]
	v_pk_add_f32 v[186:187], v[186:187], v[86:87]
	v_pk_add_f32 v[186:187], v[186:187], v[88:89]
	s_setprio 1
	s_waitcnt lgkmcnt(4)
	v_mfma_f32_32x32x16_bf16 v[50:65], v[224:227], v[170:173], v[50:65]
	v_pk_add_f32 v[90:91], v[90:91], v[0:1] op_sel_hi:[1,0] neg_lo:[0,1] neg_hi:[0,1]
	v_pk_add_f32 v[92:93], v[92:93], v[0:1] op_sel_hi:[1,0] neg_lo:[0,1] neg_hi:[0,1]
	v_exp_f32_e32 v90, v90
	v_exp_f32_e32 v91, v91
	v_mfma_f32_32x32x16_bf16 v[34:49], v[228:231], v[170:173], v[34:49]
	v_pk_add_f32 v[94:95], v[94:95], v[0:1] op_sel_hi:[1,0] neg_lo:[0,1] neg_hi:[0,1]
	v_pk_add_f32 v[96:97], v[96:97], v[0:1] op_sel_hi:[1,0] neg_lo:[0,1] neg_hi:[0,1]
	v_exp_f32_e32 v92, v92
	v_exp_f32_e32 v93, v93
	v_mfma_f32_32x32x16_bf16 v[18:33], v[232:235], v[170:173], v[18:33]
	v_exp_f32_e32 v94, v94
	v_exp_f32_e32 v95, v95
	v_exp_f32_e32 v96, v96
	v_exp_f32_e32 v97, v97
	v_cvt_pk_bf16_f32 v174, v90, v91
	v_cvt_pk_bf16_f32 v175, v92, v93
	v_mfma_f32_32x32x16_bf16 v[2:17], v[236:239], v[170:173], v[2:17]
	ds_read_b128 v[224:227], v203 offset:17472
	ds_read_b128 v[228:231], v203 offset:22080
	ds_read_b128 v[232:235], v203 offset:26688
	ds_read_b128 v[236:239], v203 offset:31296
	v_cvt_pk_bf16_f32 v176, v94, v95
	v_cvt_pk_bf16_f32 v177, v96, v97
	v_pk_add_f32 v[186:187], v[186:187], v[90:91]
	v_pk_add_f32 v[186:187], v[186:187], v[92:93]
	v_pk_add_f32 v[186:187], v[186:187], v[94:95]
	v_pk_add_f32 v[186:187], v[186:187], v[96:97]
	s_waitcnt lgkmcnt(4)
	v_mfma_f32_32x32x16_bf16 v[50:65], v[240:243], v[174:177], v[50:65]
	v_pk_add_f32 v[66:67], v[66:67], v[0:1] op_sel_hi:[1,0] neg_lo:[0,1] neg_hi:[0,1]
	v_pk_add_f32 v[68:69], v[68:69], v[0:1] op_sel_hi:[1,0] neg_lo:[0,1] neg_hi:[0,1]
	v_exp_f32_e32 v66, v66
	v_exp_f32_e32 v67, v67
	v_mfma_f32_32x32x16_bf16 v[34:49], v[244:247], v[174:177], v[34:49]
	v_pk_add_f32 v[70:71], v[70:71], v[0:1] op_sel_hi:[1,0] neg_lo:[0,1] neg_hi:[0,1]
	v_pk_add_f32 v[72:73], v[72:73], v[0:1] op_sel_hi:[1,0] neg_lo:[0,1] neg_hi:[0,1]
	v_exp_f32_e32 v68, v68
	v_exp_f32_e32 v69, v69
	v_mfma_f32_32x32x16_bf16 v[18:33], v[248:251], v[174:177], v[18:33]
	v_exp_f32_e32 v70, v70
	v_exp_f32_e32 v71, v71
	v_exp_f32_e32 v72, v72
	v_exp_f32_e32 v73, v73
	v_cvt_pk_bf16_f32 v178, v66, v67
	v_cvt_pk_bf16_f32 v179, v68, v69
	v_mfma_f32_32x32x16_bf16 v[2:17], v[204:207], v[174:177], v[2:17]
	ds_read_b128 v[240:243], v203 offset:17504
	ds_read_b128 v[244:247], v203 offset:22112
	ds_read_b128 v[248:251], v203 offset:26720
	ds_read_b128 v[204:207], v203 offset:31328
	v_cvt_pk_bf16_f32 v180, v70, v71
	v_cvt_pk_bf16_f32 v181, v72, v73
	v_pk_add_f32 v[186:187], v[186:187], v[66:67]
	v_pk_add_f32 v[186:187], v[186:187], v[68:69]
	v_pk_add_f32 v[186:187], v[186:187], v[70:71]
	v_pk_add_f32 v[186:187], v[186:187], v[72:73]
	s_waitcnt lgkmcnt(4)
	v_mfma_f32_32x32x16_bf16 v[50:65], v[224:227], v[178:181], v[50:65]
	v_pk_add_f32 v[74:75], v[74:75], v[0:1] op_sel_hi:[1,0] neg_lo:[0,1] neg_hi:[0,1]
	v_pk_add_f32 v[76:77], v[76:77], v[0:1] op_sel_hi:[1,0] neg_lo:[0,1] neg_hi:[0,1]
	v_exp_f32_e32 v74, v74
	v_exp_f32_e32 v75, v75
	v_mfma_f32_32x32x16_bf16 v[34:49], v[228:231], v[178:181], v[34:49]
	v_pk_add_f32 v[78:79], v[78:79], v[0:1] op_sel_hi:[1,0] neg_lo:[0,1] neg_hi:[0,1]
	v_pk_add_f32 v[80:81], v[80:81], v[0:1] op_sel_hi:[1,0] neg_lo:[0,1] neg_hi:[0,1]
	v_exp_f32_e32 v76, v76
	v_exp_f32_e32 v77, v77
	v_mfma_f32_32x32x16_bf16 v[18:33], v[232:235], v[178:181], v[18:33]
	v_exp_f32_e32 v78, v78
	v_exp_f32_e32 v79, v79
	v_exp_f32_e32 v80, v80
	v_exp_f32_e32 v81, v81
	v_cvt_pk_bf16_f32 v182, v74, v75
	v_cvt_pk_bf16_f32 v183, v76, v77
	v_mfma_f32_32x32x16_bf16 v[2:17], v[236:239], v[178:181], v[2:17]
	v_cvt_pk_bf16_f32 v184, v78, v79
	v_cvt_pk_bf16_f32 v185, v80, v81
	v_pk_add_f32 v[186:187], v[186:187], v[74:75]
	v_pk_add_f32 v[186:187], v[186:187], v[76:77]
	v_pk_add_f32 v[186:187], v[186:187], v[78:79]
	v_pk_add_f32 v[186:187], v[186:187], v[80:81]
	s_waitcnt lgkmcnt(0)
	v_mfma_f32_32x32x16_bf16 v[50:65], v[240:243], v[182:185], v[50:65]
	v_mfma_f32_32x32x16_bf16 v[34:49], v[244:247], v[182:185], v[34:49]
	v_mfma_f32_32x32x16_bf16 v[18:33], v[248:251], v[182:185], v[18:33]
	v_mfma_f32_32x32x16_bf16 v[2:17], v[204:207], v[182:185], v[2:17]
	s_setprio 0
	v_add_f32_e32 v186, v186, v187
	v_add_f32_e32 v131, v131, v186
	s_or_b64 exec, exec, s[64:65]
	s_andn2_b64 vcc, exec, s[62:63]
	s_cbranch_vccnz .LBB0_474
